# FFN-up GEMM with MFMA operands swapped (accumulator blocks transposed): conv3 along registers with bpermute halo rows, lane-transposed 16-byte stores
# baseline (speedup 1.0000x reference)
.LBB0_584:
	ds_read_b128 v[100:103], v193
	ds_read_b128 v[104:107], v193 offset:1024
	ds_read_b128 v[112:115], v193 offset:2048
	ds_read_b128 v[116:119], v193 offset:3072
	ds_read_b128 v[120:123], v194
	ds_read_b128 v[124:127], v194 offset:1024
	ds_read_b128 v[128:131], v194 offset:2048
	ds_read_b128 v[132:135], v194 offset:3072
	s_add_u32 s8, s10, 0x100
	s_addc_u32 s9, s11, 0
	s_cmp_eq_u32 s20, 12
	s_cselect_b32 s15, s81, s9
	s_cselect_b32 s14, s80, s8
	s_cselect_b32 s13, s1, s19
	s_cselect_b32 s12, s17, s18
	v_lshl_add_u64 v[222:223], s[10:11], 0, v[168:169]
	s_add_i32 m0, s53, 0xc000
	ds_read_b128 v[176:179], v195
	ds_read_b128 v[180:183], v195 offset:1024
	ds_read_b128 v[198:201], v195 offset:2048
	ds_read_b128 v[202:205], v195 offset:3072
	ds_read_b128 v[206:209], v195 offset:4096
	ds_read_b128 v[210:213], v195 offset:5120
	ds_read_b128 v[214:217], v195 offset:6144
	ds_read_b128 v[218:221], v195 offset:7168
	global_load_lds_dwordx4 v[222:223], off
	v_lshl_add_u64 v[222:223], s[10:11], 0, v[170:171]
	s_add_i32 m0, s53, 0xe000
	s_nop 0
	global_load_lds_dwordx4 v[222:223], off
	s_waitcnt vmcnt(8)
	s_waitcnt lgkmcnt(0)
	s_barrier
	s_setprio 1
	s_waitcnt lgkmcnt(0)
	v_mfma_f32_16x16x32_bf16 v[156:159], v[176:179], v[100:103], v[156:159]
	v_mfma_f32_16x16x32_bf16 v[148:151], v[198:201], v[100:103], v[148:151]
	v_mfma_f32_16x16x32_bf16 v[140:143], v[206:209], v[100:103], v[140:143]
	v_mfma_f32_16x16x32_bf16 v[108:111], v[214:217], v[100:103], v[108:111]
	v_mfma_f32_16x16x32_bf16 v[60:63], v[176:179], v[112:115], v[60:63]
	v_mfma_f32_16x16x32_bf16 v[52:55], v[198:201], v[112:115], v[52:55]
	v_mfma_f32_16x16x32_bf16 v[44:47], v[206:209], v[112:115], v[44:47]
	v_mfma_f32_16x16x32_bf16 v[36:39], v[214:217], v[112:115], v[36:39]
	v_mfma_f32_16x16x32_bf16 v[156:159], v[180:183], v[104:107], v[156:159]
	v_mfma_f32_16x16x32_bf16 v[148:151], v[202:205], v[104:107], v[148:151]
	v_mfma_f32_16x16x32_bf16 v[140:143], v[210:213], v[104:107], v[140:143]
	v_mfma_f32_16x16x32_bf16 v[108:111], v[218:221], v[104:107], v[108:111]
	v_mfma_f32_16x16x32_bf16 v[60:63], v[180:183], v[116:119], v[60:63]
	v_mfma_f32_16x16x32_bf16 v[52:55], v[202:205], v[116:119], v[52:55]
	v_mfma_f32_16x16x32_bf16 v[44:47], v[210:213], v[116:119], v[44:47]
	v_mfma_f32_16x16x32_bf16 v[36:39], v[218:221], v[116:119], v[36:39]
	s_setprio 0
	s_setprio 1
	v_mfma_f32_16x16x32_bf16 v[152:155], v[176:179], v[120:123], v[152:155]
	v_mfma_f32_16x16x32_bf16 v[144:147], v[198:201], v[120:123], v[144:147]
	v_mfma_f32_16x16x32_bf16 v[136:139], v[206:209], v[120:123], v[136:139]
	v_mfma_f32_16x16x32_bf16 v[96:99], v[214:217], v[120:123], v[96:99]
	v_mfma_f32_16x16x32_bf16 v[56:59], v[176:179], v[128:131], v[56:59]
	v_mfma_f32_16x16x32_bf16 v[48:51], v[198:201], v[128:131], v[48:51]
	v_mfma_f32_16x16x32_bf16 v[40:43], v[206:209], v[128:131], v[40:43]
	v_mfma_f32_16x16x32_bf16 v[32:35], v[214:217], v[128:131], v[32:35]
	v_mfma_f32_16x16x32_bf16 v[152:155], v[180:183], v[124:127], v[152:155]
	v_mfma_f32_16x16x32_bf16 v[144:147], v[202:205], v[124:127], v[144:147]
	v_mfma_f32_16x16x32_bf16 v[136:139], v[210:213], v[124:127], v[136:139]
	v_mfma_f32_16x16x32_bf16 v[96:99], v[218:221], v[124:127], v[96:99]
	v_mfma_f32_16x16x32_bf16 v[56:59], v[180:183], v[132:135], v[56:59]
	v_mfma_f32_16x16x32_bf16 v[48:51], v[202:205], v[132:135], v[48:51]
	v_mfma_f32_16x16x32_bf16 v[40:43], v[210:213], v[132:135], v[40:43]
	v_mfma_f32_16x16x32_bf16 v[32:35], v[218:221], v[132:135], v[32:35]
	s_setprio 0
	s_barrier
	s_add_i32 s10, s91, s52
	v_lshl_add_u64 v[222:223], s[12:13], 0, v[162:163]
	s_mov_b32 m0, s10
	ds_read_b128 v[176:179], v195 offset:16384
	ds_read_b128 v[180:183], v195 offset:17408
	ds_read_b128 v[198:201], v195 offset:18432
	ds_read_b128 v[202:205], v195 offset:19456
	ds_read_b128 v[206:209], v195 offset:20480
	ds_read_b128 v[210:213], v195 offset:21504
	ds_read_b128 v[214:217], v195 offset:22528
	ds_read_b128 v[218:221], v195 offset:23552
	global_load_lds_dwordx4 v[222:223], off
	s_add_i32 m0, s10, 0x2000
	s_add_u32 s10, s12, 0x580000
	v_lshl_add_u64 v[224:225], s[12:13], 0, v[166:167]
	s_addc_u32 s11, s13, 0
	s_add_i32 s21, s60, s52
	global_load_lds_dwordx4 v[224:225], off
	v_lshl_add_u64 v[226:227], s[10:11], 0, v[162:163]
	s_mov_b32 m0, s21
	v_lshl_add_u64 v[228:229], s[14:15], 0, v[164:165]
	global_load_lds_dwordx4 v[226:227], off
	v_lshl_add_u64 v[226:227], s[10:11], 0, v[166:167]
	s_add_i32 m0, s21, 0x2000
	s_nop 0
	global_load_lds_dwordx4 v[226:227], off
	v_lshl_add_u64 v[226:227], s[14:15], 0, v[160:161]
	s_mov_b32 m0, s53
	s_nop 0
	global_load_lds_dwordx4 v[226:227], off
	s_mov_b32 m0, s54
	s_nop 0
	global_load_lds_dwordx4 v[228:229], off
	s_waitcnt vmcnt(8)
	s_waitcnt lgkmcnt(0)
	s_barrier
	s_setprio 1
	s_waitcnt lgkmcnt(0)
	v_mfma_f32_16x16x32_bf16 v[92:95], v[176:179], v[100:103], v[92:95]
	v_mfma_f32_16x16x32_bf16 v[84:87], v[198:201], v[100:103], v[84:87]
	v_mfma_f32_16x16x32_bf16 v[76:79], v[206:209], v[100:103], v[76:79]
	v_mfma_f32_16x16x32_bf16 v[68:71], v[214:217], v[100:103], v[68:71]
	v_mfma_f32_16x16x32_bf16 v[28:31], v[176:179], v[112:115], v[28:31]
	v_mfma_f32_16x16x32_bf16 v[20:23], v[198:201], v[112:115], v[20:23]
	v_mfma_f32_16x16x32_bf16 v[12:15], v[206:209], v[112:115], v[12:15]
	v_mfma_f32_16x16x32_bf16 v[4:7], v[214:217], v[112:115], v[4:7]
	v_mfma_f32_16x16x32_bf16 v[92:95], v[180:183], v[104:107], v[92:95]
	v_mfma_f32_16x16x32_bf16 v[84:87], v[202:205], v[104:107], v[84:87]
	v_mfma_f32_16x16x32_bf16 v[76:79], v[210:213], v[104:107], v[76:79]
	v_mfma_f32_16x16x32_bf16 v[68:71], v[218:221], v[104:107], v[68:71]
	v_mfma_f32_16x16x32_bf16 v[28:31], v[180:183], v[116:119], v[28:31]
	v_mfma_f32_16x16x32_bf16 v[20:23], v[202:205], v[116:119], v[20:23]
	v_mfma_f32_16x16x32_bf16 v[12:15], v[210:213], v[116:119], v[12:15]
	v_mfma_f32_16x16x32_bf16 v[4:7], v[218:221], v[116:119], v[4:7]
	s_setprio 0
	s_setprio 1
	v_mfma_f32_16x16x32_bf16 v[88:91], v[176:179], v[120:123], v[88:91]
	v_mfma_f32_16x16x32_bf16 v[80:83], v[198:201], v[120:123], v[80:83]
	v_mfma_f32_16x16x32_bf16 v[72:75], v[206:209], v[120:123], v[72:75]
	v_mfma_f32_16x16x32_bf16 v[64:67], v[214:217], v[120:123], v[64:67]
	v_mfma_f32_16x16x32_bf16 v[24:27], v[176:179], v[128:131], v[24:27]
	v_mfma_f32_16x16x32_bf16 v[16:19], v[198:201], v[128:131], v[16:19]
	v_mfma_f32_16x16x32_bf16 v[8:11], v[206:209], v[128:131], v[8:11]
	v_mfma_f32_16x16x32_bf16 v[0:3], v[214:217], v[128:131], v[0:3]
	v_mfma_f32_16x16x32_bf16 v[88:91], v[180:183], v[124:127], v[88:91]
	v_mfma_f32_16x16x32_bf16 v[80:83], v[202:205], v[124:127], v[80:83]
	v_mfma_f32_16x16x32_bf16 v[72:75], v[210:213], v[124:127], v[72:75]
	v_mfma_f32_16x16x32_bf16 v[64:67], v[218:221], v[124:127], v[64:67]
	v_mfma_f32_16x16x32_bf16 v[24:27], v[180:183], v[132:135], v[24:27]
	v_mfma_f32_16x16x32_bf16 v[16:19], v[202:205], v[132:135], v[16:19]
	v_mfma_f32_16x16x32_bf16 v[8:11], v[210:213], v[132:135], v[8:11]
	v_mfma_f32_16x16x32_bf16 v[0:3], v[218:221], v[132:135], v[0:3]
	s_setprio 0
	s_barrier
	s_add_i32 s21, 0, 0x18000
	s_add_i32 s22, 0, 0x1c000
	v_add_u32_e32 v116, s21, v188
	v_add_u32_e32 v132, s22, v188
	ds_read_b128 v[100:103], v116
	ds_read_b128 v[104:107], v116 offset:1024
	ds_read_b128 v[112:115], v116 offset:2048
	ds_read_b128 v[116:119], v116 offset:3072
	ds_read_b128 v[120:123], v132
	ds_read_b128 v[124:127], v132 offset:1024
	ds_read_b128 v[128:131], v132 offset:2048
	ds_read_b128 v[132:135], v132 offset:3072
	s_add_u32 s10, s14, 0x3e000
	s_addc_u32 s11, s15, 0
	s_mov_b32 m0, s55
	v_lshl_add_u64 v[230:231], s[10:11], 0, v[160:161]
	ds_read_b128 v[176:179], v195 offset:32768
	ds_read_b128 v[180:183], v195 offset:33792
	ds_read_b128 v[198:201], v195 offset:34816
	ds_read_b128 v[202:205], v195 offset:35840
	ds_read_b128 v[206:209], v195 offset:36864
	ds_read_b128 v[210:213], v195 offset:37888
	ds_read_b128 v[214:217], v195 offset:38912
	ds_read_b128 v[218:221], v195 offset:39936
	global_load_lds_dwordx4 v[230:231], off
	v_lshl_add_u64 v[230:231], s[10:11], 0, v[164:165]
	s_mov_b32 m0, s95
	s_nop 0
	global_load_lds_dwordx4 v[230:231], off
	s_waitcnt vmcnt(8)
	s_waitcnt lgkmcnt(0)
	s_barrier
	s_setprio 1
	s_waitcnt lgkmcnt(0)
	v_mfma_f32_16x16x32_bf16 v[156:159], v[176:179], v[100:103], v[156:159]
	v_mfma_f32_16x16x32_bf16 v[148:151], v[198:201], v[100:103], v[148:151]
	v_mfma_f32_16x16x32_bf16 v[140:143], v[206:209], v[100:103], v[140:143]
	v_mfma_f32_16x16x32_bf16 v[108:111], v[214:217], v[100:103], v[108:111]
	v_mfma_f32_16x16x32_bf16 v[60:63], v[176:179], v[112:115], v[60:63]
	v_mfma_f32_16x16x32_bf16 v[52:55], v[198:201], v[112:115], v[52:55]
	v_mfma_f32_16x16x32_bf16 v[44:47], v[206:209], v[112:115], v[44:47]
	v_mfma_f32_16x16x32_bf16 v[36:39], v[214:217], v[112:115], v[36:39]
	v_mfma_f32_16x16x32_bf16 v[156:159], v[180:183], v[104:107], v[156:159]
	v_mfma_f32_16x16x32_bf16 v[148:151], v[202:205], v[104:107], v[148:151]
	v_mfma_f32_16x16x32_bf16 v[140:143], v[210:213], v[104:107], v[140:143]
	v_mfma_f32_16x16x32_bf16 v[108:111], v[218:221], v[104:107], v[108:111]
	v_mfma_f32_16x16x32_bf16 v[60:63], v[180:183], v[116:119], v[60:63]
	v_mfma_f32_16x16x32_bf16 v[52:55], v[202:205], v[116:119], v[52:55]
	v_mfma_f32_16x16x32_bf16 v[44:47], v[210:213], v[116:119], v[44:47]
	v_mfma_f32_16x16x32_bf16 v[36:39], v[218:221], v[116:119], v[36:39]
	s_setprio 0
	s_setprio 1
	v_mfma_f32_16x16x32_bf16 v[152:155], v[176:179], v[120:123], v[152:155]
	v_mfma_f32_16x16x32_bf16 v[144:147], v[198:201], v[120:123], v[144:147]
	v_mfma_f32_16x16x32_bf16 v[136:139], v[206:209], v[120:123], v[136:139]
	v_mfma_f32_16x16x32_bf16 v[96:99], v[214:217], v[120:123], v[96:99]
	v_mfma_f32_16x16x32_bf16 v[56:59], v[176:179], v[128:131], v[56:59]
	v_mfma_f32_16x16x32_bf16 v[48:51], v[198:201], v[128:131], v[48:51]
	v_mfma_f32_16x16x32_bf16 v[40:43], v[206:209], v[128:131], v[40:43]
	v_mfma_f32_16x16x32_bf16 v[32:35], v[214:217], v[128:131], v[32:35]
	v_mfma_f32_16x16x32_bf16 v[152:155], v[180:183], v[124:127], v[152:155]
	v_mfma_f32_16x16x32_bf16 v[144:147], v[202:205], v[124:127], v[144:147]
	v_mfma_f32_16x16x32_bf16 v[136:139], v[210:213], v[124:127], v[136:139]
	v_mfma_f32_16x16x32_bf16 v[96:99], v[218:221], v[124:127], v[96:99]
	v_mfma_f32_16x16x32_bf16 v[56:59], v[180:183], v[132:135], v[56:59]
	v_mfma_f32_16x16x32_bf16 v[48:51], v[202:205], v[132:135], v[48:51]
	v_mfma_f32_16x16x32_bf16 v[40:43], v[210:213], v[132:135], v[40:43]
	v_mfma_f32_16x16x32_bf16 v[32:35], v[218:221], v[132:135], v[32:35]
	s_setprio 0
	s_barrier
	s_add_i32 s10, s21, s52
	v_lshl_add_u64 v[222:223], v[222:223], 0, s[56:57]
	s_mov_b32 m0, s10
	ds_read_b128 v[176:179], v195 offset:49152
	ds_read_b128 v[180:183], v195 offset:50176
	ds_read_b128 v[198:201], v195 offset:51200
	ds_read_b128 v[202:205], v195 offset:52224
	ds_read_b128 v[206:209], v195 offset:53248
	ds_read_b128 v[210:213], v195 offset:54272
	ds_read_b128 v[214:217], v195 offset:55296
	ds_read_b128 v[218:221], v195 offset:56320
	global_load_lds_dwordx4 v[222:223], off
	s_add_i32 m0, s10, 0x2000
	s_add_u32 s10, s12, 0x580080
	v_lshl_add_u64 v[222:223], v[224:225], 0, s[56:57]
	s_addc_u32 s11, s13, 0
	s_add_i32 s12, s22, s52
	global_load_lds_dwordx4 v[222:223], off
	v_lshl_add_u64 v[222:223], s[10:11], 0, v[162:163]
	s_mov_b32 m0, s12
	s_nop 0
	global_load_lds_dwordx4 v[222:223], off
	v_lshl_add_u64 v[222:223], s[10:11], 0, v[166:167]
	s_add_i32 m0, s12, 0x2000
	s_nop 0
	global_load_lds_dwordx4 v[222:223], off
	v_lshl_add_u64 v[222:223], v[226:227], 0, s[56:57]
	s_mov_b32 m0, s89
	s_nop 0
	global_load_lds_dwordx4 v[222:223], off
	v_lshl_add_u64 v[222:223], v[228:229], 0, s[56:57]
	s_mov_b32 m0, s90
	s_nop 0
	global_load_lds_dwordx4 v[222:223], off
	s_waitcnt vmcnt(8)
	s_waitcnt lgkmcnt(0)
	s_barrier
	s_setprio 1
	s_waitcnt lgkmcnt(0)
	v_mfma_f32_16x16x32_bf16 v[92:95], v[176:179], v[100:103], v[92:95]
	v_mfma_f32_16x16x32_bf16 v[84:87], v[198:201], v[100:103], v[84:87]
	v_mfma_f32_16x16x32_bf16 v[76:79], v[206:209], v[100:103], v[76:79]
	v_mfma_f32_16x16x32_bf16 v[68:71], v[214:217], v[100:103], v[68:71]
	v_mfma_f32_16x16x32_bf16 v[28:31], v[176:179], v[112:115], v[28:31]
	v_mfma_f32_16x16x32_bf16 v[20:23], v[198:201], v[112:115], v[20:23]
	v_mfma_f32_16x16x32_bf16 v[12:15], v[206:209], v[112:115], v[12:15]
	v_mfma_f32_16x16x32_bf16 v[4:7], v[214:217], v[112:115], v[4:7]
	v_mfma_f32_16x16x32_bf16 v[92:95], v[180:183], v[104:107], v[92:95]
	v_mfma_f32_16x16x32_bf16 v[84:87], v[202:205], v[104:107], v[84:87]
	v_mfma_f32_16x16x32_bf16 v[76:79], v[210:213], v[104:107], v[76:79]
	v_mfma_f32_16x16x32_bf16 v[68:71], v[218:221], v[104:107], v[68:71]
	v_mfma_f32_16x16x32_bf16 v[28:31], v[180:183], v[116:119], v[28:31]
	v_mfma_f32_16x16x32_bf16 v[20:23], v[202:205], v[116:119], v[20:23]
	v_mfma_f32_16x16x32_bf16 v[12:15], v[210:213], v[116:119], v[12:15]
	v_mfma_f32_16x16x32_bf16 v[4:7], v[218:221], v[116:119], v[4:7]
	s_setprio 0
	s_setprio 1
	v_mfma_f32_16x16x32_bf16 v[88:91], v[176:179], v[120:123], v[88:91]
	v_mfma_f32_16x16x32_bf16 v[80:83], v[198:201], v[120:123], v[80:83]
	v_mfma_f32_16x16x32_bf16 v[72:75], v[206:209], v[120:123], v[72:75]
	v_mfma_f32_16x16x32_bf16 v[64:67], v[214:217], v[120:123], v[64:67]
	v_mfma_f32_16x16x32_bf16 v[24:27], v[176:179], v[128:131], v[24:27]
	v_mfma_f32_16x16x32_bf16 v[16:19], v[198:201], v[128:131], v[16:19]
	v_mfma_f32_16x16x32_bf16 v[8:11], v[206:209], v[128:131], v[8:11]
	v_mfma_f32_16x16x32_bf16 v[0:3], v[214:217], v[128:131], v[0:3]
	v_mfma_f32_16x16x32_bf16 v[88:91], v[180:183], v[124:127], v[88:91]
	v_mfma_f32_16x16x32_bf16 v[80:83], v[202:205], v[124:127], v[80:83]
	v_mfma_f32_16x16x32_bf16 v[72:75], v[210:213], v[124:127], v[72:75]
	v_mfma_f32_16x16x32_bf16 v[64:67], v[218:221], v[124:127], v[64:67]
	v_mfma_f32_16x16x32_bf16 v[24:27], v[180:183], v[132:135], v[24:27]
	v_mfma_f32_16x16x32_bf16 v[16:19], v[202:205], v[132:135], v[16:19]
	v_mfma_f32_16x16x32_bf16 v[8:11], v[210:213], v[132:135], v[8:11]
	v_mfma_f32_16x16x32_bf16 v[0:3], v[218:221], v[132:135], v[0:3]
	s_setprio 0
	s_barrier
	s_add_i32 s20, s20, 2
	s_add_u32 s18, s18, 0x100
	s_addc_u32 s19, s19, 0
	s_cmp_gt_u32 s20, 13
	s_mov_b64 s[10:11], s[8:9]
	s_cbranch_scc0 .LBB0_584
	v_readlane_b32 s8, v254, 2
	v_readlane_b32 s9, v254, 3
	s_and_b64 vcc, exec, s[8:9]
	s_cbranch_vccz .LBB0_587
	s_barrier
.LBB0_587:
	v_readlane_b32 s12, v254, 22
	v_readlane_b32 s13, v254, 23
	v_readlane_b32 s22, v254, 24
	v_readlane_b32 s23, v254, 25
	v_readlane_b32 s15, v254, 44
	v_and_b32_e32 v244, 12, v187
	v_lshlrev_b32_e32 v244, 1, v244
	v_and_b32_e32 v245, 0x60, v192
	v_lshl_or_b32 v245, s0, 7, v245
	v_or_b32_e32 v250, v245, v244
	v_and_b32_e32 v253, 3, v187
	v_or3_b32 v245, v245, v244, v253
	v_lshlrev_b32_e32 v245, 2, v245
	s_mul_hi_i32 s0, s16, 0x78787879
	s_lshr_b32 s1, s0, 31
	s_ashr_i32 s0, s0, 3
	s_add_i32 s0, s0, s1
	s_mul_i32 s1, s0, 17
	s_sub_i32 s1, s16, s1
	s_mul_i32 s14, s1, 0xf8
	global_load_dword v112, v245, s[70:71]
	global_load_dword v113, v245, s[66:67]
	global_load_dword v114, v245, s[12:13]
	global_load_dword v116, v245, s[22:23]
	global_load_dword v118, v245, s[72:73]
	global_load_dword v119, v245, s[68:69]
	global_load_dword v120, v245, s[62:63]
	global_load_dword v122, v245, s[76:77]
	global_load_dword v124, v245, s[70:71] offset:16
	global_load_dword v125, v245, s[66:67] offset:16
	global_load_dword v126, v245, s[12:13] offset:16
	global_load_dword v128, v245, s[22:23] offset:16
	global_load_dword v130, v245, s[72:73] offset:16
	global_load_dword v131, v245, s[68:69] offset:16
	global_load_dword v132, v245, s[62:63] offset:16
	global_load_dword v134, v245, s[76:77] offset:16
	s_add_i32 s14, s14, s15
	s_lshl_b32 s8, s0, 12
	s_add_i32 s8, s8, s14
	v_bfe_u32 v244, v186, 4, 2
	v_lshl_or_b32 v244, v244, 2, v253
	v_cmp_lt_u32_e64 s[36:37], 1, v244
	v_add_u32_e32 v251, s14, v244
	v_add_u32_e32 v244, s8, v244
	v_lshlrev_b32_e32 v250, 1, v250
	v_mad_u32_u24 v250, v244, s74, v250
	v_add_u32_e32 v252, 48, v184
	v_and_b32_e32 v252, 63, v252
	v_lshlrev_b32_e32 v252, 2, v252
	v_and_b32_e32 v244, 1, v184
	v_cmp_eq_u32_e32 vcc, 1, v244
	v_mov_b32_e32 v253, 0x5040100
	v_mov_b32_e32 v244, 0x3020706
	s_nop 0
	v_cndmask_b32_e32 v253, v253, v244, vcc
	s_mov_b32 s28, 0
	s_mov_b32 s29, 0xffff0000
	s_mov_b32 s30, 0xcccccccc
	s_mov_b32 s31, 0xcccccccc
	s_mov_b32 s34, 0xffff
	s_mov_b32 s35, 0
	v_mov_b32_e32 v246, 0xc0135761
	v_mov_b32_e32 v247, 0xc0135761
	v_mov_b32_e32 v248, 0xbdd2d3e8
	v_mov_b32_e32 v249, 0xbdd2d3e8
	s_cmp_lg_u32 s14, 0
	s_cbranch_scc1 .Lffn_nz
	v_cndmask_b32_e64 v156, v156, 0, s[34:35]
	v_cndmask_b32_e64 v157, v157, 0, s[34:35]
	v_cndmask_b32_e64 v152, v152, 0, s[34:35]
	v_cndmask_b32_e64 v153, v153, 0, s[34:35]
	v_cndmask_b32_e64 v60, v60, 0, s[34:35]
	v_cndmask_b32_e64 v61, v61, 0, s[34:35]
	v_cndmask_b32_e64 v56, v56, 0, s[34:35]
	v_cndmask_b32_e64 v57, v57, 0, s[34:35]
	s_nop 1
.Lffn_nz:
	s_waitcnt vmcnt(0)
	ds_bpermute_b32 v200, v252, v158
	ds_bpermute_b32 v201, v252, v159
	ds_bpermute_b32 v202, v252, v154
	ds_bpermute_b32 v203, v252, v155
	s_waitcnt lgkmcnt(0)
	ds_bpermute_b32 v204, v252, v62
	ds_bpermute_b32 v205, v252, v63
	ds_bpermute_b32 v206, v252, v58
	ds_bpermute_b32 v207, v252, v59
	v_pk_fma_f32 v[230:231], v[156:157], v[112:113], v[116:117] op_sel_hi:[1,0,0]
	v_pk_fma_f32 v[232:233], v[158:159], v[112:113], v[116:117] op_sel_hi:[1,0,0]
	v_fmac_f32_e32 v230, v201, v113
	v_fmac_f32_e32 v231, v156, v113
	v_fmac_f32_e32 v232, v157, v113
	v_fmac_f32_e32 v233, v158, v113
	v_pk_fma_f32 v[230:231], v[200:201], v[114:115], v[230:231] op_sel_hi:[1,0,1]
	v_pk_fma_f32 v[232:233], v[156:157], v[114:115], v[232:233] op_sel_hi:[1,0,1]
	v_pk_fma_f32 v[234:235], v[152:153], v[118:119], v[122:123] op_sel_hi:[1,0,0]
	v_pk_fma_f32 v[236:237], v[154:155], v[118:119], v[122:123] op_sel_hi:[1,0,0]
	v_fmac_f32_e32 v234, v203, v119
	v_fmac_f32_e32 v235, v152, v119
	v_fmac_f32_e32 v236, v153, v119
	v_fmac_f32_e32 v237, v154, v119
	v_pk_fma_f32 v[234:235], v[202:203], v[120:121], v[234:235] op_sel_hi:[1,0,1]
	v_pk_fma_f32 v[236:237], v[152:153], v[120:121], v[236:237] op_sel_hi:[1,0,1]
	v_pk_mul_f32 v[238:239], v[230:231], v[230:231]
	v_pk_mul_f32 v[240:241], v[232:233], v[232:233]
	v_pk_fma_f32 v[238:239], v[238:239], v[248:249], v[246:247]
	v_pk_fma_f32 v[240:241], v[240:241], v[248:249], v[246:247]
	v_pk_mul_f32 v[238:239], v[230:231], v[238:239]
	v_pk_mul_f32 v[240:241], v[232:233], v[240:241]
	v_exp_f32_e32 v238, v238
	v_exp_f32_e32 v239, v239
	v_exp_f32_e32 v240, v240
	v_exp_f32_e32 v241, v241
	v_pk_add_f32 v[238:239], v[238:239], 1.0 op_sel_hi:[1,0]
	v_pk_add_f32 v[240:241], v[240:241], 1.0 op_sel_hi:[1,0]
	v_rcp_f32_e32 v238, v238
	v_rcp_f32_e32 v239, v239
	v_rcp_f32_e32 v240, v240
	v_rcp_f32_e32 v241, v241
	v_pk_mul_f32 v[230:231], v[230:231], v[234:235]
	v_pk_mul_f32 v[232:233], v[232:233], v[236:237]
	v_pk_mul_f32 v[238:239], v[230:231], v[238:239]
	v_pk_mul_f32 v[240:241], v[232:233], v[240:241]
	v_cvt_pk_bf16_f32 v212, v238, v239
	v_cvt_pk_bf16_f32 v213, v240, v241
	s_mov_b64 vcc, s[30:31]
	s_nop 0
	v_mov_b32_dpp v214, v212 quad_perm:[1,0,3,2] row_mask:0xf bank_mask:0xf
	v_mov_b32_dpp v215, v213 quad_perm:[1,0,3,2] row_mask:0xf bank_mask:0xf
	v_perm_b32 v216, v214, v212, v253
	v_perm_b32 v217, v215, v213, v253
	s_nop 1
	v_mov_b32_dpp v218, v216 quad_perm:[2,3,0,1] row_mask:0xf bank_mask:0xf
	v_mov_b32_dpp v219, v217 quad_perm:[2,3,0,1] row_mask:0xf bank_mask:0xf
	v_cndmask_b32_e32 v176, v216, v219, vcc
	v_cndmask_b32_e32 v177, v218, v217, vcc
	s_waitcnt lgkmcnt(0)
	s_mov_b64 vcc, s[28:29]
	v_cndmask_b32_e32 v208, v150, v158, vcc
	v_cndmask_b32_e32 v209, v151, v159, vcc
	v_cndmask_b32_e32 v210, v146, v154, vcc
	v_cndmask_b32_e32 v211, v147, v155, vcc
	ds_bpermute_b32 v200, v252, v208
	ds_bpermute_b32 v201, v252, v209
	ds_bpermute_b32 v202, v252, v210
	ds_bpermute_b32 v203, v252, v211
	v_pk_fma_f32 v[230:231], v[60:61], v[124:125], v[128:129] op_sel_hi:[1,0,0]
	v_pk_fma_f32 v[232:233], v[62:63], v[124:125], v[128:129] op_sel_hi:[1,0,0]
	v_fmac_f32_e32 v230, v205, v125
	v_fmac_f32_e32 v231, v60, v125
	v_fmac_f32_e32 v232, v61, v125
	v_fmac_f32_e32 v233, v62, v125
	v_pk_fma_f32 v[230:231], v[204:205], v[126:127], v[230:231] op_sel_hi:[1,0,1]
	v_pk_fma_f32 v[232:233], v[60:61], v[126:127], v[232:233] op_sel_hi:[1,0,1]
	v_pk_fma_f32 v[234:235], v[56:57], v[130:131], v[134:135] op_sel_hi:[1,0,0]
	v_pk_fma_f32 v[236:237], v[58:59], v[130:131], v[134:135] op_sel_hi:[1,0,0]
	v_fmac_f32_e32 v234, v207, v131
	v_fmac_f32_e32 v235, v56, v131
	v_fmac_f32_e32 v236, v57, v131
	v_fmac_f32_e32 v237, v58, v131
	v_pk_fma_f32 v[234:235], v[206:207], v[132:133], v[234:235] op_sel_hi:[1,0,1]
	v_pk_fma_f32 v[236:237], v[56:57], v[132:133], v[236:237] op_sel_hi:[1,0,1]
	v_pk_mul_f32 v[238:239], v[230:231], v[230:231]
	v_pk_mul_f32 v[240:241], v[232:233], v[232:233]
	v_pk_fma_f32 v[238:239], v[238:239], v[248:249], v[246:247]
	v_pk_fma_f32 v[240:241], v[240:241], v[248:249], v[246:247]
	v_pk_mul_f32 v[238:239], v[230:231], v[238:239]
	v_pk_mul_f32 v[240:241], v[232:233], v[240:241]
	v_exp_f32_e32 v238, v238
	v_exp_f32_e32 v239, v239
	v_exp_f32_e32 v240, v240
	v_exp_f32_e32 v241, v241
	v_pk_add_f32 v[238:239], v[238:239], 1.0 op_sel_hi:[1,0]
	v_pk_add_f32 v[240:241], v[240:241], 1.0 op_sel_hi:[1,0]
	v_rcp_f32_e32 v238, v238
	v_rcp_f32_e32 v239, v239
	v_rcp_f32_e32 v240, v240
	v_rcp_f32_e32 v241, v241
	v_pk_mul_f32 v[230:231], v[230:231], v[234:235]
	v_pk_mul_f32 v[232:233], v[232:233], v[236:237]
	v_pk_mul_f32 v[238:239], v[230:231], v[238:239]
	v_pk_mul_f32 v[240:241], v[232:233], v[240:241]
	v_cvt_pk_bf16_f32 v212, v238, v239
	v_cvt_pk_bf16_f32 v213, v240, v241
	s_mov_b64 vcc, s[30:31]
	s_nop 0
	v_mov_b32_dpp v214, v212 quad_perm:[1,0,3,2] row_mask:0xf bank_mask:0xf
	v_mov_b32_dpp v215, v213 quad_perm:[1,0,3,2] row_mask:0xf bank_mask:0xf
	v_perm_b32 v216, v214, v212, v253
	v_perm_b32 v217, v215, v213, v253
	s_nop 1
	v_mov_b32_dpp v218, v216 quad_perm:[2,3,0,1] row_mask:0xf bank_mask:0xf
	v_mov_b32_dpp v219, v217 quad_perm:[2,3,0,1] row_mask:0xf bank_mask:0xf
	v_cndmask_b32_e32 v178, v216, v219, vcc
	v_cndmask_b32_e32 v179, v218, v217, vcc
	s_movk_i32 s15, 0x1002
	v_cmp_gt_i32_e64 s[24:25], s15, v251
	s_sub_u32 s84, s58, 0x2c00
	s_subb_u32 s85, s59, 0
	s_and_b64 s[24:25], s[24:25], s[36:37]
	s_mov_b64 exec, s[24:25]
	global_store_dwordx4 v250, v[176:179], s[84:85]
	s_mov_b64 exec, -1
	s_nop 0
	s_waitcnt lgkmcnt(0)
	s_mov_b64 vcc, s[28:29]
	v_cndmask_b32_e32 v208, v54, v62, vcc
	v_cndmask_b32_e32 v209, v55, v63, vcc
	v_cndmask_b32_e32 v210, v50, v58, vcc
	v_cndmask_b32_e32 v211, v51, v59, vcc
	ds_bpermute_b32 v204, v252, v208
	ds_bpermute_b32 v205, v252, v209
	ds_bpermute_b32 v206, v252, v210
	ds_bpermute_b32 v207, v252, v211
	v_pk_fma_f32 v[230:231], v[148:149], v[112:113], v[116:117] op_sel_hi:[1,0,0]
	v_pk_fma_f32 v[232:233], v[150:151], v[112:113], v[116:117] op_sel_hi:[1,0,0]
	v_fmac_f32_e32 v230, v201, v113
	v_fmac_f32_e32 v231, v148, v113
	v_fmac_f32_e32 v232, v149, v113
	v_fmac_f32_e32 v233, v150, v113
	v_pk_fma_f32 v[230:231], v[200:201], v[114:115], v[230:231] op_sel_hi:[1,0,1]
	v_pk_fma_f32 v[232:233], v[148:149], v[114:115], v[232:233] op_sel_hi:[1,0,1]
	v_pk_fma_f32 v[234:235], v[144:145], v[118:119], v[122:123] op_sel_hi:[1,0,0]
	v_pk_fma_f32 v[236:237], v[146:147], v[118:119], v[122:123] op_sel_hi:[1,0,0]
	v_fmac_f32_e32 v234, v203, v119
	v_fmac_f32_e32 v235, v144, v119
	v_fmac_f32_e32 v236, v145, v119
	v_fmac_f32_e32 v237, v146, v119
	v_pk_fma_f32 v[234:235], v[202:203], v[120:121], v[234:235] op_sel_hi:[1,0,1]
	v_pk_fma_f32 v[236:237], v[144:145], v[120:121], v[236:237] op_sel_hi:[1,0,1]
	v_pk_mul_f32 v[238:239], v[230:231], v[230:231]
	v_pk_mul_f32 v[240:241], v[232:233], v[232:233]
	v_pk_fma_f32 v[238:239], v[238:239], v[248:249], v[246:247]
	v_pk_fma_f32 v[240:241], v[240:241], v[248:249], v[246:247]
	v_pk_mul_f32 v[238:239], v[230:231], v[238:239]
	v_pk_mul_f32 v[240:241], v[232:233], v[240:241]
	v_exp_f32_e32 v238, v238
	v_exp_f32_e32 v239, v239
	v_exp_f32_e32 v240, v240
	v_exp_f32_e32 v241, v241
	v_pk_add_f32 v[238:239], v[238:239], 1.0 op_sel_hi:[1,0]
	v_pk_add_f32 v[240:241], v[240:241], 1.0 op_sel_hi:[1,0]
	v_rcp_f32_e32 v238, v238
	v_rcp_f32_e32 v239, v239
	v_rcp_f32_e32 v240, v240
	v_rcp_f32_e32 v241, v241
	v_pk_mul_f32 v[230:231], v[230:231], v[234:235]
	v_pk_mul_f32 v[232:233], v[232:233], v[236:237]
	v_pk_mul_f32 v[238:239], v[230:231], v[238:239]
	v_pk_mul_f32 v[240:241], v[232:233], v[240:241]
	v_cvt_pk_bf16_f32 v212, v238, v239
	v_cvt_pk_bf16_f32 v213, v240, v241
	s_mov_b64 vcc, s[30:31]
	s_nop 0
	v_mov_b32_dpp v214, v212 quad_perm:[1,0,3,2] row_mask:0xf bank_mask:0xf
	v_mov_b32_dpp v215, v213 quad_perm:[1,0,3,2] row_mask:0xf bank_mask:0xf
	v_perm_b32 v216, v214, v212, v253
	v_perm_b32 v217, v215, v213, v253
	s_nop 1
	v_mov_b32_dpp v218, v216 quad_perm:[2,3,0,1] row_mask:0xf bank_mask:0xf
	v_mov_b32_dpp v219, v217 quad_perm:[2,3,0,1] row_mask:0xf bank_mask:0xf
	v_cndmask_b32_e32 v180, v216, v219, vcc
	v_cndmask_b32_e32 v181, v218, v217, vcc
	s_waitcnt lgkmcnt(0)
	s_mov_b64 vcc, s[28:29]
	v_cndmask_b32_e32 v208, v142, v150, vcc
	v_cndmask_b32_e32 v209, v143, v151, vcc
	v_cndmask_b32_e32 v210, v138, v146, vcc
	v_cndmask_b32_e32 v211, v139, v147, vcc
	ds_bpermute_b32 v200, v252, v208
	ds_bpermute_b32 v201, v252, v209
	ds_bpermute_b32 v202, v252, v210
	ds_bpermute_b32 v203, v252, v211
	v_pk_fma_f32 v[230:231], v[52:53], v[124:125], v[128:129] op_sel_hi:[1,0,0]
	v_pk_fma_f32 v[232:233], v[54:55], v[124:125], v[128:129] op_sel_hi:[1,0,0]
	v_fmac_f32_e32 v230, v205, v125
	v_fmac_f32_e32 v231, v52, v125
	v_fmac_f32_e32 v232, v53, v125
	v_fmac_f32_e32 v233, v54, v125
	v_pk_fma_f32 v[230:231], v[204:205], v[126:127], v[230:231] op_sel_hi:[1,0,1]
	v_pk_fma_f32 v[232:233], v[52:53], v[126:127], v[232:233] op_sel_hi:[1,0,1]
	v_pk_fma_f32 v[234:235], v[48:49], v[130:131], v[134:135] op_sel_hi:[1,0,0]
	v_pk_fma_f32 v[236:237], v[50:51], v[130:131], v[134:135] op_sel_hi:[1,0,0]
	v_fmac_f32_e32 v234, v207, v131
	v_fmac_f32_e32 v235, v48, v131
	v_fmac_f32_e32 v236, v49, v131
	v_fmac_f32_e32 v237, v50, v131
	v_pk_fma_f32 v[234:235], v[206:207], v[132:133], v[234:235] op_sel_hi:[1,0,1]
	v_pk_fma_f32 v[236:237], v[48:49], v[132:133], v[236:237] op_sel_hi:[1,0,1]
	v_pk_mul_f32 v[238:239], v[230:231], v[230:231]
	v_pk_mul_f32 v[240:241], v[232:233], v[232:233]
	v_pk_fma_f32 v[238:239], v[238:239], v[248:249], v[246:247]
	v_pk_fma_f32 v[240:241], v[240:241], v[248:249], v[246:247]
	v_pk_mul_f32 v[238:239], v[230:231], v[238:239]
	v_pk_mul_f32 v[240:241], v[232:233], v[240:241]
	v_exp_f32_e32 v238, v238
	v_exp_f32_e32 v239, v239
	v_exp_f32_e32 v240, v240
	v_exp_f32_e32 v241, v241
	v_pk_add_f32 v[238:239], v[238:239], 1.0 op_sel_hi:[1,0]
	v_pk_add_f32 v[240:241], v[240:241], 1.0 op_sel_hi:[1,0]
	v_rcp_f32_e32 v238, v238
	v_rcp_f32_e32 v239, v239
	v_rcp_f32_e32 v240, v240
	v_rcp_f32_e32 v241, v241
	v_pk_mul_f32 v[230:231], v[230:231], v[234:235]
	v_pk_mul_f32 v[232:233], v[232:233], v[236:237]
	v_pk_mul_f32 v[238:239], v[230:231], v[238:239]
	v_pk_mul_f32 v[240:241], v[232:233], v[240:241]
	v_cvt_pk_bf16_f32 v212, v238, v239
	v_cvt_pk_bf16_f32 v213, v240, v241
	s_mov_b64 vcc, s[30:31]
	s_nop 0
	v_mov_b32_dpp v214, v212 quad_perm:[1,0,3,2] row_mask:0xf bank_mask:0xf
	v_mov_b32_dpp v215, v213 quad_perm:[1,0,3,2] row_mask:0xf bank_mask:0xf
	v_perm_b32 v216, v214, v212, v253
	v_perm_b32 v217, v215, v213, v253
	s_nop 1
	v_mov_b32_dpp v218, v216 quad_perm:[2,3,0,1] row_mask:0xf bank_mask:0xf
	v_mov_b32_dpp v219, v217 quad_perm:[2,3,0,1] row_mask:0xf bank_mask:0xf
	v_cndmask_b32_e32 v182, v216, v219, vcc
	v_cndmask_b32_e32 v183, v218, v217, vcc
	s_movk_i32 s15, 0xff2
	v_cmp_gt_i32_e64 s[24:25], s15, v251
	s_add_u32 s84, s58, 0x13400
	s_addc_u32 s85, s59, 0
	s_mov_b64 exec, s[24:25]
	global_store_dwordx4 v250, v[180:183], s[84:85]
	s_mov_b64 exec, -1
	s_nop 0
	s_waitcnt lgkmcnt(0)
	s_mov_b64 vcc, s[28:29]
	v_cndmask_b32_e32 v208, v46, v54, vcc
	v_cndmask_b32_e32 v209, v47, v55, vcc
	v_cndmask_b32_e32 v210, v42, v50, vcc
	v_cndmask_b32_e32 v211, v43, v51, vcc
	ds_bpermute_b32 v204, v252, v208
	ds_bpermute_b32 v205, v252, v209
	ds_bpermute_b32 v206, v252, v210
	ds_bpermute_b32 v207, v252, v211
	v_pk_fma_f32 v[230:231], v[140:141], v[112:113], v[116:117] op_sel_hi:[1,0,0]
	v_pk_fma_f32 v[232:233], v[142:143], v[112:113], v[116:117] op_sel_hi:[1,0,0]
	v_fmac_f32_e32 v230, v201, v113
	v_fmac_f32_e32 v231, v140, v113
	v_fmac_f32_e32 v232, v141, v113
	v_fmac_f32_e32 v233, v142, v113
	v_pk_fma_f32 v[230:231], v[200:201], v[114:115], v[230:231] op_sel_hi:[1,0,1]
	v_pk_fma_f32 v[232:233], v[140:141], v[114:115], v[232:233] op_sel_hi:[1,0,1]
	v_pk_fma_f32 v[234:235], v[136:137], v[118:119], v[122:123] op_sel_hi:[1,0,0]
	v_pk_fma_f32 v[236:237], v[138:139], v[118:119], v[122:123] op_sel_hi:[1,0,0]
	v_fmac_f32_e32 v234, v203, v119
	v_fmac_f32_e32 v235, v136, v119
	v_fmac_f32_e32 v236, v137, v119
	v_fmac_f32_e32 v237, v138, v119
	v_pk_fma_f32 v[234:235], v[202:203], v[120:121], v[234:235] op_sel_hi:[1,0,1]
	v_pk_fma_f32 v[236:237], v[136:137], v[120:121], v[236:237] op_sel_hi:[1,0,1]
	v_pk_mul_f32 v[238:239], v[230:231], v[230:231]
	v_pk_mul_f32 v[240:241], v[232:233], v[232:233]
	v_pk_fma_f32 v[238:239], v[238:239], v[248:249], v[246:247]
	v_pk_fma_f32 v[240:241], v[240:241], v[248:249], v[246:247]
	v_pk_mul_f32 v[238:239], v[230:231], v[238:239]
	v_pk_mul_f32 v[240:241], v[232:233], v[240:241]
	v_exp_f32_e32 v238, v238
	v_exp_f32_e32 v239, v239
	v_exp_f32_e32 v240, v240
	v_exp_f32_e32 v241, v241
	v_pk_add_f32 v[238:239], v[238:239], 1.0 op_sel_hi:[1,0]
	v_pk_add_f32 v[240:241], v[240:241], 1.0 op_sel_hi:[1,0]
	v_rcp_f32_e32 v238, v238
	v_rcp_f32_e32 v239, v239
	v_rcp_f32_e32 v240, v240
	v_rcp_f32_e32 v241, v241
	v_pk_mul_f32 v[230:231], v[230:231], v[234:235]
	v_pk_mul_f32 v[232:233], v[232:233], v[236:237]
	v_pk_mul_f32 v[238:239], v[230:231], v[238:239]
	v_pk_mul_f32 v[240:241], v[232:233], v[240:241]
	v_cvt_pk_bf16_f32 v212, v238, v239
	v_cvt_pk_bf16_f32 v213, v240, v241
	s_mov_b64 vcc, s[30:31]
	s_nop 0
	v_mov_b32_dpp v214, v212 quad_perm:[1,0,3,2] row_mask:0xf bank_mask:0xf
	v_mov_b32_dpp v215, v213 quad_perm:[1,0,3,2] row_mask:0xf bank_mask:0xf
	v_perm_b32 v216, v214, v212, v253
	v_perm_b32 v217, v215, v213, v253
	s_nop 1
	v_mov_b32_dpp v218, v216 quad_perm:[2,3,0,1] row_mask:0xf bank_mask:0xf
	v_mov_b32_dpp v219, v217 quad_perm:[2,3,0,1] row_mask:0xf bank_mask:0xf
	v_cndmask_b32_e32 v176, v216, v219, vcc
	v_cndmask_b32_e32 v177, v218, v217, vcc
	s_waitcnt lgkmcnt(0)
	s_mov_b64 vcc, s[28:29]
	v_cndmask_b32_e32 v208, v110, v142, vcc
	v_cndmask_b32_e32 v209, v111, v143, vcc
	v_cndmask_b32_e32 v210, v98, v138, vcc
	v_cndmask_b32_e32 v211, v99, v139, vcc
	ds_bpermute_b32 v200, v252, v208
	ds_bpermute_b32 v201, v252, v209
	ds_bpermute_b32 v202, v252, v210
	ds_bpermute_b32 v203, v252, v211
	v_pk_fma_f32 v[230:231], v[44:45], v[124:125], v[128:129] op_sel_hi:[1,0,0]
	v_pk_fma_f32 v[232:233], v[46:47], v[124:125], v[128:129] op_sel_hi:[1,0,0]
	v_fmac_f32_e32 v230, v205, v125
	v_fmac_f32_e32 v231, v44, v125
	v_fmac_f32_e32 v232, v45, v125
	v_fmac_f32_e32 v233, v46, v125
	v_pk_fma_f32 v[230:231], v[204:205], v[126:127], v[230:231] op_sel_hi:[1,0,1]
	v_pk_fma_f32 v[232:233], v[44:45], v[126:127], v[232:233] op_sel_hi:[1,0,1]
	v_pk_fma_f32 v[234:235], v[40:41], v[130:131], v[134:135] op_sel_hi:[1,0,0]
	v_pk_fma_f32 v[236:237], v[42:43], v[130:131], v[134:135] op_sel_hi:[1,0,0]
	v_fmac_f32_e32 v234, v207, v131
	v_fmac_f32_e32 v235, v40, v131
	v_fmac_f32_e32 v236, v41, v131
	v_fmac_f32_e32 v237, v42, v131
	v_pk_fma_f32 v[234:235], v[206:207], v[132:133], v[234:235] op_sel_hi:[1,0,1]
	v_pk_fma_f32 v[236:237], v[40:41], v[132:133], v[236:237] op_sel_hi:[1,0,1]
	v_pk_mul_f32 v[238:239], v[230:231], v[230:231]
	v_pk_mul_f32 v[240:241], v[232:233], v[232:233]
	v_pk_fma_f32 v[238:239], v[238:239], v[248:249], v[246:247]
	v_pk_fma_f32 v[240:241], v[240:241], v[248:249], v[246:247]
	v_pk_mul_f32 v[238:239], v[230:231], v[238:239]
	v_pk_mul_f32 v[240:241], v[232:233], v[240:241]
	v_exp_f32_e32 v238, v238
	v_exp_f32_e32 v239, v239
	v_exp_f32_e32 v240, v240
	v_exp_f32_e32 v241, v241
	v_pk_add_f32 v[238:239], v[238:239], 1.0 op_sel_hi:[1,0]
	v_pk_add_f32 v[240:241], v[240:241], 1.0 op_sel_hi:[1,0]
	v_rcp_f32_e32 v238, v238
	v_rcp_f32_e32 v239, v239
	v_rcp_f32_e32 v240, v240
	v_rcp_f32_e32 v241, v241
	v_pk_mul_f32 v[230:231], v[230:231], v[234:235]
	v_pk_mul_f32 v[232:233], v[232:233], v[236:237]
	v_pk_mul_f32 v[238:239], v[230:231], v[238:239]
	v_pk_mul_f32 v[240:241], v[232:233], v[240:241]
	v_cvt_pk_bf16_f32 v212, v238, v239
	v_cvt_pk_bf16_f32 v213, v240, v241
	s_mov_b64 vcc, s[30:31]
	s_nop 0
	v_mov_b32_dpp v214, v212 quad_perm:[1,0,3,2] row_mask:0xf bank_mask:0xf
	v_mov_b32_dpp v215, v213 quad_perm:[1,0,3,2] row_mask:0xf bank_mask:0xf
	v_perm_b32 v216, v214, v212, v253
	v_perm_b32 v217, v215, v213, v253
	s_nop 1
	v_mov_b32_dpp v218, v216 quad_perm:[2,3,0,1] row_mask:0xf bank_mask:0xf
	v_mov_b32_dpp v219, v217 quad_perm:[2,3,0,1] row_mask:0xf bank_mask:0xf
	v_cndmask_b32_e32 v178, v216, v219, vcc
	v_cndmask_b32_e32 v179, v218, v217, vcc
	s_movk_i32 s15, 0xfe2
	v_cmp_gt_i32_e64 s[24:25], s15, v251
	s_add_u32 s84, s58, 0x29400
	s_addc_u32 s85, s59, 0
	s_mov_b64 exec, s[24:25]
	global_store_dwordx4 v250, v[176:179], s[84:85]
	s_mov_b64 exec, -1
	s_nop 0
	s_waitcnt lgkmcnt(0)
	s_mov_b64 vcc, s[28:29]
	v_cndmask_b32_e32 v208, v38, v46, vcc
	v_cndmask_b32_e32 v209, v39, v47, vcc
	v_cndmask_b32_e32 v210, v34, v42, vcc
	v_cndmask_b32_e32 v211, v35, v43, vcc
	ds_bpermute_b32 v204, v252, v208
	ds_bpermute_b32 v205, v252, v209
	ds_bpermute_b32 v206, v252, v210
	ds_bpermute_b32 v207, v252, v211
	v_pk_fma_f32 v[230:231], v[108:109], v[112:113], v[116:117] op_sel_hi:[1,0,0]
	v_pk_fma_f32 v[232:233], v[110:111], v[112:113], v[116:117] op_sel_hi:[1,0,0]
	v_fmac_f32_e32 v230, v201, v113
	v_fmac_f32_e32 v231, v108, v113
	v_fmac_f32_e32 v232, v109, v113
	v_fmac_f32_e32 v233, v110, v113
	v_pk_fma_f32 v[230:231], v[200:201], v[114:115], v[230:231] op_sel_hi:[1,0,1]
	v_pk_fma_f32 v[232:233], v[108:109], v[114:115], v[232:233] op_sel_hi:[1,0,1]
	v_pk_fma_f32 v[234:235], v[96:97], v[118:119], v[122:123] op_sel_hi:[1,0,0]
	v_pk_fma_f32 v[236:237], v[98:99], v[118:119], v[122:123] op_sel_hi:[1,0,0]
	v_fmac_f32_e32 v234, v203, v119
	v_fmac_f32_e32 v235, v96, v119
	v_fmac_f32_e32 v236, v97, v119
	v_fmac_f32_e32 v237, v98, v119
	v_pk_fma_f32 v[234:235], v[202:203], v[120:121], v[234:235] op_sel_hi:[1,0,1]
	v_pk_fma_f32 v[236:237], v[96:97], v[120:121], v[236:237] op_sel_hi:[1,0,1]
	v_pk_mul_f32 v[238:239], v[230:231], v[230:231]
	v_pk_mul_f32 v[240:241], v[232:233], v[232:233]
	v_pk_fma_f32 v[238:239], v[238:239], v[248:249], v[246:247]
	v_pk_fma_f32 v[240:241], v[240:241], v[248:249], v[246:247]
	v_pk_mul_f32 v[238:239], v[230:231], v[238:239]
	v_pk_mul_f32 v[240:241], v[232:233], v[240:241]
	v_exp_f32_e32 v238, v238
	v_exp_f32_e32 v239, v239
	v_exp_f32_e32 v240, v240
	v_exp_f32_e32 v241, v241
	v_pk_add_f32 v[238:239], v[238:239], 1.0 op_sel_hi:[1,0]
	v_pk_add_f32 v[240:241], v[240:241], 1.0 op_sel_hi:[1,0]
	v_rcp_f32_e32 v238, v238
	v_rcp_f32_e32 v239, v239
	v_rcp_f32_e32 v240, v240
	v_rcp_f32_e32 v241, v241
	v_pk_mul_f32 v[230:231], v[230:231], v[234:235]
	v_pk_mul_f32 v[232:233], v[232:233], v[236:237]
	v_pk_mul_f32 v[238:239], v[230:231], v[238:239]
	v_pk_mul_f32 v[240:241], v[232:233], v[240:241]
	v_cvt_pk_bf16_f32 v212, v238, v239
	v_cvt_pk_bf16_f32 v213, v240, v241
	s_mov_b64 vcc, s[30:31]
	s_nop 0
	v_mov_b32_dpp v214, v212 quad_perm:[1,0,3,2] row_mask:0xf bank_mask:0xf
	v_mov_b32_dpp v215, v213 quad_perm:[1,0,3,2] row_mask:0xf bank_mask:0xf
	v_perm_b32 v216, v214, v212, v253
	v_perm_b32 v217, v215, v213, v253
	s_nop 1
	v_mov_b32_dpp v218, v216 quad_perm:[2,3,0,1] row_mask:0xf bank_mask:0xf
	v_mov_b32_dpp v219, v217 quad_perm:[2,3,0,1] row_mask:0xf bank_mask:0xf
	v_cndmask_b32_e32 v180, v216, v219, vcc
	v_cndmask_b32_e32 v181, v218, v217, vcc
	s_waitcnt lgkmcnt(0)
	ds_bpermute_b32 v200, v252, v94
	ds_bpermute_b32 v201, v252, v95
	ds_bpermute_b32 v202, v252, v90
	ds_bpermute_b32 v203, v252, v91
	v_pk_fma_f32 v[230:231], v[36:37], v[124:125], v[128:129] op_sel_hi:[1,0,0]
	v_pk_fma_f32 v[232:233], v[38:39], v[124:125], v[128:129] op_sel_hi:[1,0,0]
	v_fmac_f32_e32 v230, v205, v125
	v_fmac_f32_e32 v231, v36, v125
	v_fmac_f32_e32 v232, v37, v125
	v_fmac_f32_e32 v233, v38, v125
	v_pk_fma_f32 v[230:231], v[204:205], v[126:127], v[230:231] op_sel_hi:[1,0,1]
	v_pk_fma_f32 v[232:233], v[36:37], v[126:127], v[232:233] op_sel_hi:[1,0,1]
	v_pk_fma_f32 v[234:235], v[32:33], v[130:131], v[134:135] op_sel_hi:[1,0,0]
	v_pk_fma_f32 v[236:237], v[34:35], v[130:131], v[134:135] op_sel_hi:[1,0,0]
	v_fmac_f32_e32 v234, v207, v131
	v_fmac_f32_e32 v235, v32, v131
	v_fmac_f32_e32 v236, v33, v131
	v_fmac_f32_e32 v237, v34, v131
	v_pk_fma_f32 v[234:235], v[206:207], v[132:133], v[234:235] op_sel_hi:[1,0,1]
	v_pk_fma_f32 v[236:237], v[32:33], v[132:133], v[236:237] op_sel_hi:[1,0,1]
	v_pk_mul_f32 v[238:239], v[230:231], v[230:231]
	v_pk_mul_f32 v[240:241], v[232:233], v[232:233]
	v_pk_fma_f32 v[238:239], v[238:239], v[248:249], v[246:247]
	v_pk_fma_f32 v[240:241], v[240:241], v[248:249], v[246:247]
	v_pk_mul_f32 v[238:239], v[230:231], v[238:239]
	v_pk_mul_f32 v[240:241], v[232:233], v[240:241]
	v_exp_f32_e32 v238, v238
	v_exp_f32_e32 v239, v239
	v_exp_f32_e32 v240, v240
	v_exp_f32_e32 v241, v241
	v_pk_add_f32 v[238:239], v[238:239], 1.0 op_sel_hi:[1,0]
	v_pk_add_f32 v[240:241], v[240:241], 1.0 op_sel_hi:[1,0]
	v_rcp_f32_e32 v238, v238
	v_rcp_f32_e32 v239, v239
	v_rcp_f32_e32 v240, v240
	v_rcp_f32_e32 v241, v241
	v_pk_mul_f32 v[230:231], v[230:231], v[234:235]
	v_pk_mul_f32 v[232:233], v[232:233], v[236:237]
	v_pk_mul_f32 v[238:239], v[230:231], v[238:239]
	v_pk_mul_f32 v[240:241], v[232:233], v[240:241]
	v_cvt_pk_bf16_f32 v212, v238, v239
	v_cvt_pk_bf16_f32 v213, v240, v241
	s_mov_b64 vcc, s[30:31]
	s_nop 0
	v_mov_b32_dpp v214, v212 quad_perm:[1,0,3,2] row_mask:0xf bank_mask:0xf
	v_mov_b32_dpp v215, v213 quad_perm:[1,0,3,2] row_mask:0xf bank_mask:0xf
	v_perm_b32 v216, v214, v212, v253
	v_perm_b32 v217, v215, v213, v253
	s_nop 1
	v_mov_b32_dpp v218, v216 quad_perm:[2,3,0,1] row_mask:0xf bank_mask:0xf
	v_mov_b32_dpp v219, v217 quad_perm:[2,3,0,1] row_mask:0xf bank_mask:0xf
	v_cndmask_b32_e32 v182, v216, v219, vcc
	v_cndmask_b32_e32 v183, v218, v217, vcc
	s_movk_i32 s15, 0xfd2
	v_cmp_gt_i32_e64 s[24:25], s15, v251
	s_add_u32 s84, s58, 0x3f400
	s_addc_u32 s85, s59, 0
	s_mov_b64 exec, s[24:25]
	global_store_dwordx4 v250, v[180:183], s[84:85]
	s_mov_b64 exec, -1
	s_nop 0
	s_waitcnt lgkmcnt(0)
	ds_bpermute_b32 v204, v252, v30
	ds_bpermute_b32 v205, v252, v31
	ds_bpermute_b32 v206, v252, v26
	ds_bpermute_b32 v207, v252, v27
	v_pk_fma_f32 v[230:231], v[92:93], v[112:113], v[116:117] op_sel_hi:[1,0,0]
	v_pk_fma_f32 v[232:233], v[94:95], v[112:113], v[116:117] op_sel_hi:[1,0,0]
	v_fmac_f32_e32 v230, v201, v113
	v_fmac_f32_e32 v231, v92, v113
	v_fmac_f32_e32 v232, v93, v113
	v_fmac_f32_e32 v233, v94, v113
	v_pk_fma_f32 v[230:231], v[200:201], v[114:115], v[230:231] op_sel_hi:[1,0,1]
	v_pk_fma_f32 v[232:233], v[92:93], v[114:115], v[232:233] op_sel_hi:[1,0,1]
	v_pk_fma_f32 v[234:235], v[88:89], v[118:119], v[122:123] op_sel_hi:[1,0,0]
	v_pk_fma_f32 v[236:237], v[90:91], v[118:119], v[122:123] op_sel_hi:[1,0,0]
	v_fmac_f32_e32 v234, v203, v119
	v_fmac_f32_e32 v235, v88, v119
	v_fmac_f32_e32 v236, v89, v119
	v_fmac_f32_e32 v237, v90, v119
	v_pk_fma_f32 v[234:235], v[202:203], v[120:121], v[234:235] op_sel_hi:[1,0,1]
	v_pk_fma_f32 v[236:237], v[88:89], v[120:121], v[236:237] op_sel_hi:[1,0,1]
	v_pk_mul_f32 v[238:239], v[230:231], v[230:231]
	v_pk_mul_f32 v[240:241], v[232:233], v[232:233]
	v_pk_fma_f32 v[238:239], v[238:239], v[248:249], v[246:247]
	v_pk_fma_f32 v[240:241], v[240:241], v[248:249], v[246:247]
	v_pk_mul_f32 v[238:239], v[230:231], v[238:239]
	v_pk_mul_f32 v[240:241], v[232:233], v[240:241]
	v_exp_f32_e32 v238, v238
	v_exp_f32_e32 v239, v239
	v_exp_f32_e32 v240, v240
	v_exp_f32_e32 v241, v241
	v_pk_add_f32 v[238:239], v[238:239], 1.0 op_sel_hi:[1,0]
	v_pk_add_f32 v[240:241], v[240:241], 1.0 op_sel_hi:[1,0]
	v_rcp_f32_e32 v238, v238
	v_rcp_f32_e32 v239, v239
	v_rcp_f32_e32 v240, v240
	v_rcp_f32_e32 v241, v241
	v_pk_mul_f32 v[230:231], v[230:231], v[234:235]
	v_pk_mul_f32 v[232:233], v[232:233], v[236:237]
	v_pk_mul_f32 v[238:239], v[230:231], v[238:239]
	v_pk_mul_f32 v[240:241], v[232:233], v[240:241]
	v_cvt_pk_bf16_f32 v212, v238, v239
	v_cvt_pk_bf16_f32 v213, v240, v241
	s_mov_b64 vcc, s[30:31]
	s_nop 0
	v_mov_b32_dpp v214, v212 quad_perm:[1,0,3,2] row_mask:0xf bank_mask:0xf
	v_mov_b32_dpp v215, v213 quad_perm:[1,0,3,2] row_mask:0xf bank_mask:0xf
	v_perm_b32 v216, v214, v212, v253
	v_perm_b32 v217, v215, v213, v253
	s_nop 1
	v_mov_b32_dpp v218, v216 quad_perm:[2,3,0,1] row_mask:0xf bank_mask:0xf
	v_mov_b32_dpp v219, v217 quad_perm:[2,3,0,1] row_mask:0xf bank_mask:0xf
	v_cndmask_b32_e32 v176, v216, v219, vcc
	v_cndmask_b32_e32 v177, v218, v217, vcc
	s_waitcnt lgkmcnt(0)
	s_mov_b64 vcc, s[28:29]
	v_cndmask_b32_e32 v208, v86, v94, vcc
	v_cndmask_b32_e32 v209, v87, v95, vcc
	v_cndmask_b32_e32 v210, v82, v90, vcc
	v_cndmask_b32_e32 v211, v83, v91, vcc
	ds_bpermute_b32 v200, v252, v208
	ds_bpermute_b32 v201, v252, v209
	ds_bpermute_b32 v202, v252, v210
	ds_bpermute_b32 v203, v252, v211
	v_pk_fma_f32 v[230:231], v[28:29], v[124:125], v[128:129] op_sel_hi:[1,0,0]
	v_pk_fma_f32 v[232:233], v[30:31], v[124:125], v[128:129] op_sel_hi:[1,0,0]
	v_fmac_f32_e32 v230, v205, v125
	v_fmac_f32_e32 v231, v28, v125
	v_fmac_f32_e32 v232, v29, v125
	v_fmac_f32_e32 v233, v30, v125
	v_pk_fma_f32 v[230:231], v[204:205], v[126:127], v[230:231] op_sel_hi:[1,0,1]
	v_pk_fma_f32 v[232:233], v[28:29], v[126:127], v[232:233] op_sel_hi:[1,0,1]
	v_pk_fma_f32 v[234:235], v[24:25], v[130:131], v[134:135] op_sel_hi:[1,0,0]
	v_pk_fma_f32 v[236:237], v[26:27], v[130:131], v[134:135] op_sel_hi:[1,0,0]
	v_fmac_f32_e32 v234, v207, v131
	v_fmac_f32_e32 v235, v24, v131
	v_fmac_f32_e32 v236, v25, v131
	v_fmac_f32_e32 v237, v26, v131
	v_pk_fma_f32 v[234:235], v[206:207], v[132:133], v[234:235] op_sel_hi:[1,0,1]
	v_pk_fma_f32 v[236:237], v[24:25], v[132:133], v[236:237] op_sel_hi:[1,0,1]
	v_pk_mul_f32 v[238:239], v[230:231], v[230:231]
	v_pk_mul_f32 v[240:241], v[232:233], v[232:233]
	v_pk_fma_f32 v[238:239], v[238:239], v[248:249], v[246:247]
	v_pk_fma_f32 v[240:241], v[240:241], v[248:249], v[246:247]
	v_pk_mul_f32 v[238:239], v[230:231], v[238:239]
	v_pk_mul_f32 v[240:241], v[232:233], v[240:241]
	v_exp_f32_e32 v238, v238
	v_exp_f32_e32 v239, v239
	v_exp_f32_e32 v240, v240
	v_exp_f32_e32 v241, v241
	v_pk_add_f32 v[238:239], v[238:239], 1.0 op_sel_hi:[1,0]
	v_pk_add_f32 v[240:241], v[240:241], 1.0 op_sel_hi:[1,0]
	v_rcp_f32_e32 v238, v238
	v_rcp_f32_e32 v239, v239
	v_rcp_f32_e32 v240, v240
	v_rcp_f32_e32 v241, v241
	v_pk_mul_f32 v[230:231], v[230:231], v[234:235]
	v_pk_mul_f32 v[232:233], v[232:233], v[236:237]
	v_pk_mul_f32 v[238:239], v[230:231], v[238:239]
	v_pk_mul_f32 v[240:241], v[232:233], v[240:241]
	v_cvt_pk_bf16_f32 v212, v238, v239
	v_cvt_pk_bf16_f32 v213, v240, v241
	s_mov_b64 vcc, s[30:31]
	s_nop 0
	v_mov_b32_dpp v214, v212 quad_perm:[1,0,3,2] row_mask:0xf bank_mask:0xf
	v_mov_b32_dpp v215, v213 quad_perm:[1,0,3,2] row_mask:0xf bank_mask:0xf
	v_perm_b32 v216, v214, v212, v253
	v_perm_b32 v217, v215, v213, v253
	s_nop 1
	v_mov_b32_dpp v218, v216 quad_perm:[2,3,0,1] row_mask:0xf bank_mask:0xf
	v_mov_b32_dpp v219, v217 quad_perm:[2,3,0,1] row_mask:0xf bank_mask:0xf
	v_cndmask_b32_e32 v178, v216, v219, vcc
	v_cndmask_b32_e32 v179, v218, v217, vcc
	s_movk_i32 s15, 0xf86
	v_cmp_gt_i32_e64 s[24:25], s15, v251
	s_add_u32 s84, s58, 0xa7c00
	s_addc_u32 s85, s59, 0
	s_and_b64 s[24:25], s[24:25], s[36:37]
	s_mov_b64 exec, s[24:25]
	global_store_dwordx4 v250, v[176:179], s[84:85]
	s_mov_b64 exec, -1
	s_nop 0
	s_waitcnt lgkmcnt(0)
	s_mov_b64 vcc, s[28:29]
	v_cndmask_b32_e32 v208, v22, v30, vcc
	v_cndmask_b32_e32 v209, v23, v31, vcc
	v_cndmask_b32_e32 v210, v18, v26, vcc
	v_cndmask_b32_e32 v211, v19, v27, vcc
	ds_bpermute_b32 v204, v252, v208
	ds_bpermute_b32 v205, v252, v209
	ds_bpermute_b32 v206, v252, v210
	ds_bpermute_b32 v207, v252, v211
	v_pk_fma_f32 v[230:231], v[84:85], v[112:113], v[116:117] op_sel_hi:[1,0,0]
	v_pk_fma_f32 v[232:233], v[86:87], v[112:113], v[116:117] op_sel_hi:[1,0,0]
	v_fmac_f32_e32 v230, v201, v113
	v_fmac_f32_e32 v231, v84, v113
	v_fmac_f32_e32 v232, v85, v113
	v_fmac_f32_e32 v233, v86, v113
	v_pk_fma_f32 v[230:231], v[200:201], v[114:115], v[230:231] op_sel_hi:[1,0,1]
	v_pk_fma_f32 v[232:233], v[84:85], v[114:115], v[232:233] op_sel_hi:[1,0,1]
	v_pk_fma_f32 v[234:235], v[80:81], v[118:119], v[122:123] op_sel_hi:[1,0,0]
	v_pk_fma_f32 v[236:237], v[82:83], v[118:119], v[122:123] op_sel_hi:[1,0,0]
	v_fmac_f32_e32 v234, v203, v119
	v_fmac_f32_e32 v235, v80, v119
	v_fmac_f32_e32 v236, v81, v119
	v_fmac_f32_e32 v237, v82, v119
	v_pk_fma_f32 v[234:235], v[202:203], v[120:121], v[234:235] op_sel_hi:[1,0,1]
	v_pk_fma_f32 v[236:237], v[80:81], v[120:121], v[236:237] op_sel_hi:[1,0,1]
	v_pk_mul_f32 v[238:239], v[230:231], v[230:231]
	v_pk_mul_f32 v[240:241], v[232:233], v[232:233]
	v_pk_fma_f32 v[238:239], v[238:239], v[248:249], v[246:247]
	v_pk_fma_f32 v[240:241], v[240:241], v[248:249], v[246:247]
	v_pk_mul_f32 v[238:239], v[230:231], v[238:239]
	v_pk_mul_f32 v[240:241], v[232:233], v[240:241]
	v_exp_f32_e32 v238, v238
	v_exp_f32_e32 v239, v239
	v_exp_f32_e32 v240, v240
	v_exp_f32_e32 v241, v241
	v_pk_add_f32 v[238:239], v[238:239], 1.0 op_sel_hi:[1,0]
	v_pk_add_f32 v[240:241], v[240:241], 1.0 op_sel_hi:[1,0]
	v_rcp_f32_e32 v238, v238
	v_rcp_f32_e32 v239, v239
	v_rcp_f32_e32 v240, v240
	v_rcp_f32_e32 v241, v241
	v_pk_mul_f32 v[230:231], v[230:231], v[234:235]
	v_pk_mul_f32 v[232:233], v[232:233], v[236:237]
	v_pk_mul_f32 v[238:239], v[230:231], v[238:239]
	v_pk_mul_f32 v[240:241], v[232:233], v[240:241]
	v_cvt_pk_bf16_f32 v212, v238, v239
	v_cvt_pk_bf16_f32 v213, v240, v241
	s_mov_b64 vcc, s[30:31]
	s_nop 0
	v_mov_b32_dpp v214, v212 quad_perm:[1,0,3,2] row_mask:0xf bank_mask:0xf
	v_mov_b32_dpp v215, v213 quad_perm:[1,0,3,2] row_mask:0xf bank_mask:0xf
	v_perm_b32 v216, v214, v212, v253
	v_perm_b32 v217, v215, v213, v253
	s_nop 1
	v_mov_b32_dpp v218, v216 quad_perm:[2,3,0,1] row_mask:0xf bank_mask:0xf
	v_mov_b32_dpp v219, v217 quad_perm:[2,3,0,1] row_mask:0xf bank_mask:0xf
	v_cndmask_b32_e32 v180, v216, v219, vcc
	v_cndmask_b32_e32 v181, v218, v217, vcc
	s_waitcnt lgkmcnt(0)
	s_mov_b64 vcc, s[28:29]
	v_cndmask_b32_e32 v208, v78, v86, vcc
	v_cndmask_b32_e32 v209, v79, v87, vcc
	v_cndmask_b32_e32 v210, v74, v82, vcc
	v_cndmask_b32_e32 v211, v75, v83, vcc
	ds_bpermute_b32 v200, v252, v208
	ds_bpermute_b32 v201, v252, v209
	ds_bpermute_b32 v202, v252, v210
	ds_bpermute_b32 v203, v252, v211
	v_pk_fma_f32 v[230:231], v[20:21], v[124:125], v[128:129] op_sel_hi:[1,0,0]
	v_pk_fma_f32 v[232:233], v[22:23], v[124:125], v[128:129] op_sel_hi:[1,0,0]
	v_fmac_f32_e32 v230, v205, v125
	v_fmac_f32_e32 v231, v20, v125
	v_fmac_f32_e32 v232, v21, v125
	v_fmac_f32_e32 v233, v22, v125
	v_pk_fma_f32 v[230:231], v[204:205], v[126:127], v[230:231] op_sel_hi:[1,0,1]
	v_pk_fma_f32 v[232:233], v[20:21], v[126:127], v[232:233] op_sel_hi:[1,0,1]
	v_pk_fma_f32 v[234:235], v[16:17], v[130:131], v[134:135] op_sel_hi:[1,0,0]
	v_pk_fma_f32 v[236:237], v[18:19], v[130:131], v[134:135] op_sel_hi:[1,0,0]
	v_fmac_f32_e32 v234, v207, v131
	v_fmac_f32_e32 v235, v16, v131
	v_fmac_f32_e32 v236, v17, v131
	v_fmac_f32_e32 v237, v18, v131
	v_pk_fma_f32 v[234:235], v[206:207], v[132:133], v[234:235] op_sel_hi:[1,0,1]
	v_pk_fma_f32 v[236:237], v[16:17], v[132:133], v[236:237] op_sel_hi:[1,0,1]
	v_pk_mul_f32 v[238:239], v[230:231], v[230:231]
	v_pk_mul_f32 v[240:241], v[232:233], v[232:233]
	v_pk_fma_f32 v[238:239], v[238:239], v[248:249], v[246:247]
	v_pk_fma_f32 v[240:241], v[240:241], v[248:249], v[246:247]
	v_pk_mul_f32 v[238:239], v[230:231], v[238:239]
	v_pk_mul_f32 v[240:241], v[232:233], v[240:241]
	v_exp_f32_e32 v238, v238
	v_exp_f32_e32 v239, v239
	v_exp_f32_e32 v240, v240
	v_exp_f32_e32 v241, v241
	v_pk_add_f32 v[238:239], v[238:239], 1.0 op_sel_hi:[1,0]
	v_pk_add_f32 v[240:241], v[240:241], 1.0 op_sel_hi:[1,0]
	v_rcp_f32_e32 v238, v238
	v_rcp_f32_e32 v239, v239
	v_rcp_f32_e32 v240, v240
	v_rcp_f32_e32 v241, v241
	v_pk_mul_f32 v[230:231], v[230:231], v[234:235]
	v_pk_mul_f32 v[232:233], v[232:233], v[236:237]
	v_pk_mul_f32 v[238:239], v[230:231], v[238:239]
	v_pk_mul_f32 v[240:241], v[232:233], v[240:241]
	v_cvt_pk_bf16_f32 v212, v238, v239
	v_cvt_pk_bf16_f32 v213, v240, v241
	s_mov_b64 vcc, s[30:31]
	s_nop 0
	v_mov_b32_dpp v214, v212 quad_perm:[1,0,3,2] row_mask:0xf bank_mask:0xf
	v_mov_b32_dpp v215, v213 quad_perm:[1,0,3,2] row_mask:0xf bank_mask:0xf
	v_perm_b32 v216, v214, v212, v253
	v_perm_b32 v217, v215, v213, v253
	s_nop 1
	v_mov_b32_dpp v218, v216 quad_perm:[2,3,0,1] row_mask:0xf bank_mask:0xf
	v_mov_b32_dpp v219, v217 quad_perm:[2,3,0,1] row_mask:0xf bank_mask:0xf
	v_cndmask_b32_e32 v182, v216, v219, vcc
	v_cndmask_b32_e32 v183, v218, v217, vcc
	s_movk_i32 s15, 0xf76
	v_cmp_gt_i32_e64 s[24:25], s15, v251
	s_add_u32 s84, s58, 0xbdc00
	s_addc_u32 s85, s59, 0
	s_mov_b64 exec, s[24:25]
	global_store_dwordx4 v250, v[180:183], s[84:85]
	s_mov_b64 exec, -1
	s_nop 0
	s_waitcnt lgkmcnt(0)
	s_mov_b64 vcc, s[28:29]
	v_cndmask_b32_e32 v208, v14, v22, vcc
	v_cndmask_b32_e32 v209, v15, v23, vcc
	v_cndmask_b32_e32 v210, v10, v18, vcc
	v_cndmask_b32_e32 v211, v11, v19, vcc
	ds_bpermute_b32 v204, v252, v208
	ds_bpermute_b32 v205, v252, v209
	ds_bpermute_b32 v206, v252, v210
	ds_bpermute_b32 v207, v252, v211
	v_pk_fma_f32 v[230:231], v[76:77], v[112:113], v[116:117] op_sel_hi:[1,0,0]
	v_pk_fma_f32 v[232:233], v[78:79], v[112:113], v[116:117] op_sel_hi:[1,0,0]
	v_fmac_f32_e32 v230, v201, v113
	v_fmac_f32_e32 v231, v76, v113
	v_fmac_f32_e32 v232, v77, v113
	v_fmac_f32_e32 v233, v78, v113
	v_pk_fma_f32 v[230:231], v[200:201], v[114:115], v[230:231] op_sel_hi:[1,0,1]
	v_pk_fma_f32 v[232:233], v[76:77], v[114:115], v[232:233] op_sel_hi:[1,0,1]
	v_pk_fma_f32 v[234:235], v[72:73], v[118:119], v[122:123] op_sel_hi:[1,0,0]
	v_pk_fma_f32 v[236:237], v[74:75], v[118:119], v[122:123] op_sel_hi:[1,0,0]
	v_fmac_f32_e32 v234, v203, v119
	v_fmac_f32_e32 v235, v72, v119
	v_fmac_f32_e32 v236, v73, v119
	v_fmac_f32_e32 v237, v74, v119
	v_pk_fma_f32 v[234:235], v[202:203], v[120:121], v[234:235] op_sel_hi:[1,0,1]
	v_pk_fma_f32 v[236:237], v[72:73], v[120:121], v[236:237] op_sel_hi:[1,0,1]
	v_pk_mul_f32 v[238:239], v[230:231], v[230:231]
	v_pk_mul_f32 v[240:241], v[232:233], v[232:233]
	v_pk_fma_f32 v[238:239], v[238:239], v[248:249], v[246:247]
	v_pk_fma_f32 v[240:241], v[240:241], v[248:249], v[246:247]
	v_pk_mul_f32 v[238:239], v[230:231], v[238:239]
	v_pk_mul_f32 v[240:241], v[232:233], v[240:241]
	v_exp_f32_e32 v238, v238
	v_exp_f32_e32 v239, v239
	v_exp_f32_e32 v240, v240
	v_exp_f32_e32 v241, v241
	v_pk_add_f32 v[238:239], v[238:239], 1.0 op_sel_hi:[1,0]
	v_pk_add_f32 v[240:241], v[240:241], 1.0 op_sel_hi:[1,0]
	v_rcp_f32_e32 v238, v238
	v_rcp_f32_e32 v239, v239
	v_rcp_f32_e32 v240, v240
	v_rcp_f32_e32 v241, v241
	v_pk_mul_f32 v[230:231], v[230:231], v[234:235]
	v_pk_mul_f32 v[232:233], v[232:233], v[236:237]
	v_pk_mul_f32 v[238:239], v[230:231], v[238:239]
	v_pk_mul_f32 v[240:241], v[232:233], v[240:241]
	v_cvt_pk_bf16_f32 v212, v238, v239
	v_cvt_pk_bf16_f32 v213, v240, v241
	s_mov_b64 vcc, s[30:31]
	s_nop 0
	v_mov_b32_dpp v214, v212 quad_perm:[1,0,3,2] row_mask:0xf bank_mask:0xf
	v_mov_b32_dpp v215, v213 quad_perm:[1,0,3,2] row_mask:0xf bank_mask:0xf
	v_perm_b32 v216, v214, v212, v253
	v_perm_b32 v217, v215, v213, v253
	s_nop 1
	v_mov_b32_dpp v218, v216 quad_perm:[2,3,0,1] row_mask:0xf bank_mask:0xf
	v_mov_b32_dpp v219, v217 quad_perm:[2,3,0,1] row_mask:0xf bank_mask:0xf
	v_cndmask_b32_e32 v176, v216, v219, vcc
	v_cndmask_b32_e32 v177, v218, v217, vcc
	s_waitcnt lgkmcnt(0)
	s_mov_b64 vcc, s[28:29]
	v_cndmask_b32_e32 v208, v70, v78, vcc
	v_cndmask_b32_e32 v209, v71, v79, vcc
	v_cndmask_b32_e32 v210, v66, v74, vcc
	v_cndmask_b32_e32 v211, v67, v75, vcc
	ds_bpermute_b32 v200, v252, v208
	ds_bpermute_b32 v201, v252, v209
	ds_bpermute_b32 v202, v252, v210
	ds_bpermute_b32 v203, v252, v211
	v_pk_fma_f32 v[230:231], v[12:13], v[124:125], v[128:129] op_sel_hi:[1,0,0]
	v_pk_fma_f32 v[232:233], v[14:15], v[124:125], v[128:129] op_sel_hi:[1,0,0]
	v_fmac_f32_e32 v230, v205, v125
	v_fmac_f32_e32 v231, v12, v125
	v_fmac_f32_e32 v232, v13, v125
	v_fmac_f32_e32 v233, v14, v125
	v_pk_fma_f32 v[230:231], v[204:205], v[126:127], v[230:231] op_sel_hi:[1,0,1]
	v_pk_fma_f32 v[232:233], v[12:13], v[126:127], v[232:233] op_sel_hi:[1,0,1]
	v_pk_fma_f32 v[234:235], v[8:9], v[130:131], v[134:135] op_sel_hi:[1,0,0]
	v_pk_fma_f32 v[236:237], v[10:11], v[130:131], v[134:135] op_sel_hi:[1,0,0]
	v_fmac_f32_e32 v234, v207, v131
	v_fmac_f32_e32 v235, v8, v131
	v_fmac_f32_e32 v236, v9, v131
	v_fmac_f32_e32 v237, v10, v131
	v_pk_fma_f32 v[234:235], v[206:207], v[132:133], v[234:235] op_sel_hi:[1,0,1]
	v_pk_fma_f32 v[236:237], v[8:9], v[132:133], v[236:237] op_sel_hi:[1,0,1]
	v_pk_mul_f32 v[238:239], v[230:231], v[230:231]
	v_pk_mul_f32 v[240:241], v[232:233], v[232:233]
	v_pk_fma_f32 v[238:239], v[238:239], v[248:249], v[246:247]
	v_pk_fma_f32 v[240:241], v[240:241], v[248:249], v[246:247]
	v_pk_mul_f32 v[238:239], v[230:231], v[238:239]
	v_pk_mul_f32 v[240:241], v[232:233], v[240:241]
	v_exp_f32_e32 v238, v238
	v_exp_f32_e32 v239, v239
	v_exp_f32_e32 v240, v240
	v_exp_f32_e32 v241, v241
	v_pk_add_f32 v[238:239], v[238:239], 1.0 op_sel_hi:[1,0]
	v_pk_add_f32 v[240:241], v[240:241], 1.0 op_sel_hi:[1,0]
	v_rcp_f32_e32 v238, v238
	v_rcp_f32_e32 v239, v239
	v_rcp_f32_e32 v240, v240
	v_rcp_f32_e32 v241, v241
	v_pk_mul_f32 v[230:231], v[230:231], v[234:235]
	v_pk_mul_f32 v[232:233], v[232:233], v[236:237]
	v_pk_mul_f32 v[238:239], v[230:231], v[238:239]
	v_pk_mul_f32 v[240:241], v[232:233], v[240:241]
	v_cvt_pk_bf16_f32 v212, v238, v239
	v_cvt_pk_bf16_f32 v213, v240, v241
	s_mov_b64 vcc, s[30:31]
	s_nop 0
	v_mov_b32_dpp v214, v212 quad_perm:[1,0,3,2] row_mask:0xf bank_mask:0xf
	v_mov_b32_dpp v215, v213 quad_perm:[1,0,3,2] row_mask:0xf bank_mask:0xf
	v_perm_b32 v216, v214, v212, v253
	v_perm_b32 v217, v215, v213, v253
	s_nop 1
	v_mov_b32_dpp v218, v216 quad_perm:[2,3,0,1] row_mask:0xf bank_mask:0xf
	v_mov_b32_dpp v219, v217 quad_perm:[2,3,0,1] row_mask:0xf bank_mask:0xf
	v_cndmask_b32_e32 v178, v216, v219, vcc
	v_cndmask_b32_e32 v179, v218, v217, vcc
	s_movk_i32 s15, 0xf66
	v_cmp_gt_i32_e64 s[24:25], s15, v251
	s_add_u32 s84, s58, 0xd3c00
	s_addc_u32 s85, s59, 0
	s_mov_b64 exec, s[24:25]
	global_store_dwordx4 v250, v[176:179], s[84:85]
	s_mov_b64 exec, -1
	s_nop 0
	s_waitcnt lgkmcnt(0)
	s_mov_b64 vcc, s[28:29]
	v_cndmask_b32_e32 v208, v6, v14, vcc
	v_cndmask_b32_e32 v209, v7, v15, vcc
	v_cndmask_b32_e32 v210, v2, v10, vcc
	v_cndmask_b32_e32 v211, v3, v11, vcc
	ds_bpermute_b32 v204, v252, v208
	ds_bpermute_b32 v205, v252, v209
	ds_bpermute_b32 v206, v252, v210
	ds_bpermute_b32 v207, v252, v211
	v_pk_fma_f32 v[230:231], v[68:69], v[112:113], v[116:117] op_sel_hi:[1,0,0]
	v_pk_fma_f32 v[232:233], v[70:71], v[112:113], v[116:117] op_sel_hi:[1,0,0]
	v_fmac_f32_e32 v230, v201, v113
	v_fmac_f32_e32 v231, v68, v113
	v_fmac_f32_e32 v232, v69, v113
	v_fmac_f32_e32 v233, v70, v113
	v_pk_fma_f32 v[230:231], v[200:201], v[114:115], v[230:231] op_sel_hi:[1,0,1]
	v_pk_fma_f32 v[232:233], v[68:69], v[114:115], v[232:233] op_sel_hi:[1,0,1]
	v_pk_fma_f32 v[234:235], v[64:65], v[118:119], v[122:123] op_sel_hi:[1,0,0]
	v_pk_fma_f32 v[236:237], v[66:67], v[118:119], v[122:123] op_sel_hi:[1,0,0]
	v_fmac_f32_e32 v234, v203, v119
	v_fmac_f32_e32 v235, v64, v119
	v_fmac_f32_e32 v236, v65, v119
	v_fmac_f32_e32 v237, v66, v119
	v_pk_fma_f32 v[234:235], v[202:203], v[120:121], v[234:235] op_sel_hi:[1,0,1]
	v_pk_fma_f32 v[236:237], v[64:65], v[120:121], v[236:237] op_sel_hi:[1,0,1]
	v_pk_mul_f32 v[238:239], v[230:231], v[230:231]
	v_pk_mul_f32 v[240:241], v[232:233], v[232:233]
	v_pk_fma_f32 v[238:239], v[238:239], v[248:249], v[246:247]
	v_pk_fma_f32 v[240:241], v[240:241], v[248:249], v[246:247]
	v_pk_mul_f32 v[238:239], v[230:231], v[238:239]
	v_pk_mul_f32 v[240:241], v[232:233], v[240:241]
	v_exp_f32_e32 v238, v238
	v_exp_f32_e32 v239, v239
	v_exp_f32_e32 v240, v240
	v_exp_f32_e32 v241, v241
	v_pk_add_f32 v[238:239], v[238:239], 1.0 op_sel_hi:[1,0]
	v_pk_add_f32 v[240:241], v[240:241], 1.0 op_sel_hi:[1,0]
	v_rcp_f32_e32 v238, v238
	v_rcp_f32_e32 v239, v239
	v_rcp_f32_e32 v240, v240
	v_rcp_f32_e32 v241, v241
	v_pk_mul_f32 v[230:231], v[230:231], v[234:235]
	v_pk_mul_f32 v[232:233], v[232:233], v[236:237]
	v_pk_mul_f32 v[238:239], v[230:231], v[238:239]
	v_pk_mul_f32 v[240:241], v[232:233], v[240:241]
	v_cvt_pk_bf16_f32 v212, v238, v239
	v_cvt_pk_bf16_f32 v213, v240, v241
	s_mov_b64 vcc, s[30:31]
	s_nop 0
	v_mov_b32_dpp v214, v212 quad_perm:[1,0,3,2] row_mask:0xf bank_mask:0xf
	v_mov_b32_dpp v215, v213 quad_perm:[1,0,3,2] row_mask:0xf bank_mask:0xf
	v_perm_b32 v216, v214, v212, v253
	v_perm_b32 v217, v215, v213, v253
	s_nop 1
	v_mov_b32_dpp v218, v216 quad_perm:[2,3,0,1] row_mask:0xf bank_mask:0xf
	v_mov_b32_dpp v219, v217 quad_perm:[2,3,0,1] row_mask:0xf bank_mask:0xf
	v_cndmask_b32_e32 v180, v216, v219, vcc
	v_cndmask_b32_e32 v181, v218, v217, vcc
	s_waitcnt lgkmcnt(0)
	v_pk_fma_f32 v[230:231], v[4:5], v[124:125], v[128:129] op_sel_hi:[1,0,0]
	v_pk_fma_f32 v[232:233], v[6:7], v[124:125], v[128:129] op_sel_hi:[1,0,0]
	v_fmac_f32_e32 v230, v205, v125
	v_fmac_f32_e32 v231, v4, v125
	v_fmac_f32_e32 v232, v5, v125
	v_fmac_f32_e32 v233, v6, v125
	v_pk_fma_f32 v[230:231], v[204:205], v[126:127], v[230:231] op_sel_hi:[1,0,1]
	v_pk_fma_f32 v[232:233], v[4:5], v[126:127], v[232:233] op_sel_hi:[1,0,1]
	v_pk_fma_f32 v[234:235], v[0:1], v[130:131], v[134:135] op_sel_hi:[1,0,0]
	v_pk_fma_f32 v[236:237], v[2:3], v[130:131], v[134:135] op_sel_hi:[1,0,0]
	v_fmac_f32_e32 v234, v207, v131
	v_fmac_f32_e32 v235, v0, v131
	v_fmac_f32_e32 v236, v1, v131
	v_fmac_f32_e32 v237, v2, v131
	v_pk_fma_f32 v[234:235], v[206:207], v[132:133], v[234:235] op_sel_hi:[1,0,1]
	v_pk_fma_f32 v[236:237], v[0:1], v[132:133], v[236:237] op_sel_hi:[1,0,1]
	v_pk_mul_f32 v[238:239], v[230:231], v[230:231]
	v_pk_mul_f32 v[240:241], v[232:233], v[232:233]
	v_pk_fma_f32 v[238:239], v[238:239], v[248:249], v[246:247]
	v_pk_fma_f32 v[240:241], v[240:241], v[248:249], v[246:247]
	v_pk_mul_f32 v[238:239], v[230:231], v[238:239]
	v_pk_mul_f32 v[240:241], v[232:233], v[240:241]
	v_exp_f32_e32 v238, v238
	v_exp_f32_e32 v239, v239
	v_exp_f32_e32 v240, v240
	v_exp_f32_e32 v241, v241
	v_pk_add_f32 v[238:239], v[238:239], 1.0 op_sel_hi:[1,0]
	v_pk_add_f32 v[240:241], v[240:241], 1.0 op_sel_hi:[1,0]
	v_rcp_f32_e32 v238, v238
	v_rcp_f32_e32 v239, v239
	v_rcp_f32_e32 v240, v240
	v_rcp_f32_e32 v241, v241
	v_pk_mul_f32 v[230:231], v[230:231], v[234:235]
	v_pk_mul_f32 v[232:233], v[232:233], v[236:237]
	v_pk_mul_f32 v[238:239], v[230:231], v[238:239]
	v_pk_mul_f32 v[240:241], v[232:233], v[240:241]
	v_cvt_pk_bf16_f32 v212, v238, v239
	v_cvt_pk_bf16_f32 v213, v240, v241
	s_mov_b64 vcc, s[30:31]
	s_nop 0
	v_mov_b32_dpp v214, v212 quad_perm:[1,0,3,2] row_mask:0xf bank_mask:0xf
	v_mov_b32_dpp v215, v213 quad_perm:[1,0,3,2] row_mask:0xf bank_mask:0xf
	v_perm_b32 v216, v214, v212, v253
	v_perm_b32 v217, v215, v213, v253
	s_nop 1
	v_mov_b32_dpp v218, v216 quad_perm:[2,3,0,1] row_mask:0xf bank_mask:0xf
	v_mov_b32_dpp v219, v217 quad_perm:[2,3,0,1] row_mask:0xf bank_mask:0xf
	v_cndmask_b32_e32 v182, v216, v219, vcc
	v_cndmask_b32_e32 v183, v218, v217, vcc
	s_movk_i32 s15, 0xf56
	v_cmp_gt_i32_e64 s[24:25], s15, v251
	s_add_u32 s84, s58, 0xe9c00
	s_addc_u32 s85, s59, 0
	s_mov_b64 exec, s[24:25]
	global_store_dwordx4 v250, v[180:183], s[84:85]
	s_mov_b64 exec, -1
	s_nop 0
	s_mov_b64 s[0:1], -1
	s_branch .LBB0_619
	s_nop 0
	s_nop 0
	s_nop 0
	s_nop 0
	s_nop 0
	s_nop 0
	s_nop 0
	s_nop 0
	s_nop 0
	s_nop 0
	s_nop 0
	s_nop 0
	s_nop 0
	s_nop 0
	s_nop 0
	s_nop 0
	s_nop 0
	s_nop 0
	s_nop 0
	s_nop 0
	s_nop 0
	s_nop 0
	s_nop 0
	s_nop 0
	s_nop 0
	s_nop 0
	s_nop 0
	s_nop 0
	s_nop 0
	s_nop 0
	s_nop 0
	s_nop 0
	s_nop 0
	s_nop 0
	s_nop 0
	s_nop 0
	s_nop 0
	s_nop 0
	s_nop 0
	s_nop 0
	s_nop 0
	s_nop 0
	s_nop 0
	s_nop 0
	s_nop 0
	s_nop 0
	s_nop 0
	s_nop 0
	s_nop 0
	s_nop 0
	s_nop 0
	s_nop 0
	s_nop 0
	s_nop 0
	s_nop 0
	s_nop 0
	s_nop 0
	s_nop 0
	s_nop 0
	s_nop 0
	s_nop 0
	s_nop 0
	s_nop 0
	s_nop 0
	s_nop 0
	s_nop 0
	s_nop 0
	s_nop 0
	s_nop 0
	s_nop 0
	s_nop 0
	s_nop 0
	s_nop 0
	s_nop 0
	s_nop 0
	s_nop 0
	s_nop 0
	s_nop 0
	s_nop 0
	s_nop 0
	s_nop 0
	s_nop 0
	s_nop 0
	s_nop 0
	s_nop 0
	s_nop 0
	s_nop 0
	s_nop 0
	s_nop 0
	s_nop 0
	s_nop 0
	s_nop 0
	s_nop 0
	s_nop 0
	s_nop 0
	s_nop 0
	s_nop 0
	s_nop 0
	s_nop 0
	s_nop 0
	s_nop 0
	s_nop 0
	s_nop 0
	s_nop 0
	s_nop 0
	s_nop 0
	s_nop 0
	s_nop 0
	s_nop 0
	s_nop 0
	s_nop 0
	s_nop 0
	s_nop 0
	s_nop 0
	s_nop 0
	s_nop 0
	s_nop 0
	s_nop 0
	s_nop 0
	s_nop 0
	s_nop 0
	s_nop 0
	s_nop 0
	s_nop 0
	s_nop 0
	s_nop 0
	s_nop 0
	s_nop 0
	s_nop 0
	s_nop 0
	s_nop 0
	s_nop 0
	s_nop 0
	s_nop 0
	s_nop 0
	s_nop 0
	s_nop 0
	s_nop 0
	s_nop 0
	s_nop 0
	s_nop 0
	s_nop 0
	s_nop 0
	s_nop 0
	s_nop 0
	s_nop 0
	s_nop 0
	s_nop 0
	s_nop 0
	s_nop 0
	s_nop 0
	s_nop 0
	s_nop 0
	s_nop 0
	s_nop 0
	s_nop 0
	s_nop 0
	s_nop 0
	s_nop 0
	s_nop 0
	s_nop 0
	s_nop 0
	s_nop 0
	s_nop 0
	s_nop 0
	s_nop 0
	s_nop 0
	s_nop 0
	s_nop 0
	s_nop 0
	s_nop 0
	s_nop 0
	s_nop 0
	s_nop 0
	s_nop 0
	s_nop 0
	s_nop 0
	s_nop 0
	s_nop 0
	s_nop 0
	s_nop 0
	s_nop 0
	s_nop 0
	s_nop 0
	s_nop 0
	s_nop 0
	s_nop 0
	s_nop 0
	s_nop 0
	s_nop 0
	s_nop 0
	s_nop 0
	s_nop 0
	s_nop 0
	s_nop 0
	s_nop 0
	s_nop 0
	s_nop 0
	s_nop 0
	s_nop 0
	s_nop 0
	s_nop 0
	s_nop 0
	s_nop 0
	s_nop 0
	s_nop 0
	s_nop 0
	s_nop 0
	s_nop 0
	s_nop 0
